# NA loop bias section: 32 batched bias reads + fma + select straight into score registers (replaces 16 exec-masked serialized read/wait blocks, 32 fills and 32 copy-back moves)
# speedup vs baseline: 1.0162x; 1.0162x over previous
; __device__ __forceinline__ void finishSM(f32x16& p0, f32x16& p1, float alpha, float& l_reg, bf16x8& pa0, bf16x8& pa1, bf16x8& pa2, bf16x8& pa3) {
; #pragma unroll
;   for (int r = 0; r < 16; ++r) p1[r] = __builtin_amdgcn_exp2f(p1[r]);
;   float ps = 0;
; #pragma unroll
;   for (int r = 0; r < 16; ++r) ps += p0[r];
; #pragma unroll
;   for (int r = 0; r < 16; ++r) ps += p1[r];
;   { auto rr = __builtin_amdgcn_permlane32_swap(__float_as_uint(ps), __float_as_uint(ps), false, false);
;     ps = __uint_as_float(rr[0]) + __uint_as_float(rr[1]); }
;   l_reg = l_reg * alpha + ps;
;     ...
;   PK4(p0, 0, pa0); PK4(p0, 8, pa1); PK4(p1, 0, pa2); PK4(p1, 8, pa3);
; template <int DQK> __device__ __forceinline__ void qkt(f32x16& p0, f32x16& p1, const char* Ks, const bf16x8* qr, int r32, int hi) {
;   p0 = f32x16{}; p1 = f32x16{};
; #pragma unroll
;   for (int d0 = 0; d0 < DQK / 16; ++d0) { int cb = (d0 * 16 + hi * 8) * 2;
;     bf16x8 b0 = *reinterpret_cast<const bf16x8*>(Ks + KSWZ(r32, cb));
;     bf16x8 b1 = *reinterpret_cast<const bf16x8*>(Ks + KSWZ(32 + r32, cb));
;     p0 = __builtin_amdgcn_mfma_f32_32x32x16_bf16(b0, qr[d0], p0, 0, 0, 0);
;     p1 = __builtin_amdgcn_mfma_f32_32x32x16_bf16(b1, qr[d0], p1, 0, 0, 0); }
; }
.LBB0_781:
	ds_read_b128 v[32:35], v134 offset:49152
	ds_read_b128 v[36:39], v134 offset:57344
	ds_read_b128 v[156:159], v135 offset:49152
	ds_read_b128 v[160:163], v135 offset:57344
	v_exp_f32_e32 v155, v96
	v_add_f32_e32 v96, 0, v152
	s_waitcnt lgkmcnt(3)
	v_mfma_f32_32x32x16_bf16 v[48:63], v[32:35], v[76:79], 0
	v_add_f32_e32 v96, v154, v96
	v_add_f32_e32 v96, v150, v96
	v_add_f32_e32 v96, v153, v96
	v_add_f32_e32 v96, v148, v96
	v_add_f32_e32 v96, v151, v96
	v_add_f32_e32 v96, v147, v96
	v_add_f32_e32 v96, v149, v96
	s_waitcnt lgkmcnt(2)
	v_mfma_f32_32x32x16_bf16 v[32:47], v[36:39], v[76:79], 0
	v_add_f32_e32 v96, v111, v96
	v_add_f32_e32 v96, v146, v96
	v_add_f32_e32 v96, v109, v96
	v_add_f32_e32 v96, v143, v96
	v_exp_f32_e32 v105, v102
	v_add_f32_e32 v96, v107, v96
	v_exp_f32_e32 v142, v103
	s_waitcnt lgkmcnt(1)
	v_mfma_f32_32x32x16_bf16 v[48:63], v[156:159], v[72:75], v[48:63]
	v_add_f32_e32 v96, v110, v96
	v_exp_f32_e32 v144, v100
	v_add_f32_e32 v96, v106, v96
	v_exp_f32_e32 v145, v101
	v_add_f32_e32 v96, v108, v96
	v_add_f32_e32 v96, v105, v96
	v_add_f32_e32 v96, v142, v96
	s_waitcnt lgkmcnt(0)
	v_mfma_f32_32x32x16_bf16 v[32:47], v[160:163], v[72:75], v[32:47]
	ds_read_b128 v[156:159], v136 offset:49152
	ds_read_b128 v[160:163], v136 offset:57344
	v_exp_f32_e32 v92, v92
	v_add_f32_e32 v96, v144, v96
	v_exp_f32_e32 v93, v93
	v_add_f32_e32 v96, v145, v96
	v_exp_f32_e32 v88, v88
	v_add_f32_e32 v96, v155, v96
	s_waitcnt lgkmcnt(1)
	v_mfma_f32_32x32x16_bf16 v[48:63], v[156:159], v[68:71], v[48:63]
	v_exp_f32_e32 v89, v89
	v_exp_f32_e32 v94, v94
	v_exp_f32_e32 v95, v95
	v_exp_f32_e32 v90, v90
	v_exp_f32_e32 v91, v91
	s_waitcnt lgkmcnt(0)
	v_mfma_f32_32x32x16_bf16 v[32:47], v[160:163], v[68:71], v[32:47]
	ds_read_b128 v[156:159], v137 offset:49152
	ds_read_b128 v[160:163], v137 offset:57344
	s_waitcnt lgkmcnt(1)
	v_mfma_f32_32x32x16_bf16 v[48:63], v[156:159], v[64:67], v[48:63]
	v_exp_f32_e32 v156, v97
	v_exp_f32_e32 v157, v98
	v_exp_f32_e32 v158, v99
	v_add_f32_e32 v96, v156, v96
	v_add_f32_e32 v96, v92, v96
	v_add_f32_e32 v96, v93, v96
	v_add_f32_e32 v96, v88, v96
	v_add_f32_e32 v96, v89, v96
	s_waitcnt lgkmcnt(0)
	v_mfma_f32_32x32x16_bf16 v[32:47], v[160:163], v[64:67], v[32:47]
	v_add_f32_e32 v96, v157, v96
	v_add_f32_e32 v96, v158, v96
	v_add_f32_e32 v96, v94, v96
	v_add_f32_e32 v96, v95, v96
	v_add_f32_e32 v96, v90, v96
	v_add_f32_e32 v140, v91, v96
	v_mov_b32_e32 v141, v140
	s_nop 1
	v_permlane32_swap_b32_e32 v140, v141
	v_cvt_pk_bf16_f32 v96, v152, v154
	v_cvt_pk_bf16_f32 v97, v150, v153
	v_cvt_pk_bf16_f32 v98, v148, v151
	v_cvt_pk_bf16_f32 v99, v147, v149
	v_cvt_pk_bf16_f32 v100, v111, v146
	v_cvt_pk_bf16_f32 v101, v109, v143
	v_cvt_pk_bf16_f32 v102, v107, v110
	v_cvt_pk_bf16_f32 v103, v106, v108
	v_cvt_pk_bf16_f32 v106, v105, v142
	v_cvt_pk_bf16_f32 v107, v144, v145
	v_cvt_pk_bf16_f32 v108, v155, v156
	v_cvt_pk_bf16_f32 v109, v92, v93
	v_cvt_pk_bf16_f32 v142, v88, v89
	v_cvt_pk_bf16_f32 v143, v157, v158
	v_cvt_pk_bf16_f32 v144, v94, v95
	v_cvt_pk_bf16_f32 v145, v90, v91
	s_nop 0
	v_permlane32_swap_b32_e32 v96, v98
	v_permlane32_swap_b32_e32 v97, v99
	v_permlane32_swap_b32_e32 v100, v102
	v_permlane32_swap_b32_e32 v101, v103
	v_permlane32_swap_b32_e32 v106, v108
	v_permlane32_swap_b32_e32 v107, v109
	v_permlane32_swap_b32_e32 v142, v144
	v_permlane32_swap_b32_e32 v143, v145
	s_sub_i32 s0, s78, 64
	s_cmp_lt_u32 s3, 2
	s_cselect_b32 s0, s76, s0
	s_ashr_i32 s1, s0, 31
	v_lshl_add_u64 v[88:89], s[0:1], 0, v[114:115]
	v_mad_u64_u32 v[90:91], s[0:1], v88, s86, v[116:117]
	v_mad_u64_u32 v[92:93], s[0:1], v88, s86, v[118:119]
	v_mad_i32_i24 v91, v89, s86, v91
	v_mad_i32_i24 v93, v89, s86, v93
	global_load_dwordx4 v[88:91], v[90:91], off
	s_nop 0
	global_load_dwordx4 v[92:95], v[92:93], off
	ds_read_b64_tr_b16 v[146:147], v128 offset:0
	ds_read_b64_tr_b16 v[148:149], v128 offset:0x800
	ds_read_b64_tr_b16 v[150:151], v128 offset:0x1000
	ds_read_b64_tr_b16 v[152:153], v128 offset:0x1800
	ds_read_b64_tr_b16 v[154:155], v128 offset:0x2000
	ds_read_b64_tr_b16 v[156:157], v128 offset:0x2800
	ds_read_b64_tr_b16 v[158:159], v128 offset:0x3000
	ds_read_b64_tr_b16 v[160:161], v128 offset:0x3800
	s_waitcnt lgkmcnt(0)
	s_nop 0
	v_mfma_f32_32x32x16_bf16 v[0:15], v[96:99], v[146:149], v[0:15]
	ds_read_b64_tr_b16 v[146:147], v128 offset:0x200
	ds_read_b64_tr_b16 v[148:149], v128 offset:0xa00
	v_mfma_f32_32x32x16_bf16 v[0:15], v[100:103], v[150:153], v[0:15]
	ds_read_b64_tr_b16 v[150:151], v128 offset:0x1200
	ds_read_b64_tr_b16 v[152:153], v128 offset:0x1a00
	v_mfma_f32_32x32x16_bf16 v[0:15], v[106:109], v[154:157], v[0:15]
	ds_read_b64_tr_b16 v[154:155], v128 offset:0x2200
	ds_read_b64_tr_b16 v[156:157], v128 offset:0x2a00
	v_mfma_f32_32x32x16_bf16 v[0:15], v[142:145], v[158:161], v[0:15]
	ds_read_b64_tr_b16 v[158:159], v128 offset:0x3200
	ds_read_b64_tr_b16 v[160:161], v128 offset:0x3a00
	s_waitcnt lgkmcnt(0)
	v_mfma_f32_32x32x16_bf16 v[16:31], v[96:99], v[146:149], v[16:31]
	v_mfma_f32_32x32x16_bf16 v[16:31], v[100:103], v[150:153], v[16:31]
	v_mfma_f32_32x32x16_bf16 v[16:31], v[106:109], v[154:157], v[16:31]
	v_mfma_f32_32x32x16_bf16 v[16:31], v[142:145], v[158:161], v[16:31]
	s_cmp_lt_u32 s3, 4
	s_cbranch_scc1 .LBB0_817
; #define SBAR() __builtin_amdgcn_sched_barrier(0)
; __device__ __forceinline__ void na_bias(f32x16& p0, f32x16& p1, const NaInfo& na, int kr, int hi) {
;   const int rs = min(max(na.qr - 4, 0), 120);
;   if (kr < rs || kr >= rs + 8) {
; #pragma unroll
;     for (int r = 0; r < 16; ++r) { p0[r] = -1e30f; p1[r] = -1e30f; }
;   } else {
;     const float* b = na.brow + (kr - na.qr + 7) * 31 + (15 - na.qc) + 4 * hi;
;     const int ws = min(max(na.qc - 8, 0), 48) - 4 * hi;
; #pragma unroll
;     for (int r = 0; r < 16; ++r) {
;       const int kc0 = (r & 3) + 8 * (r >> 2);
;       const bool ok1 = (unsigned)(kc0 - ws) < 16u, ok2 = (unsigned)(kc0 + 32 - ws) < 16u;
;       const float b1 = b[kc0], b2 = b[kc0 + 32];
;       p0[r] = ok1 ? p0[r] + 8.0f * b1 : -1e30f;
;       p1[r] = ok2 ? p1[r] + 8.0f * b2 : -1e30f;
;       if ((r & 3) == 3) SBAR();
;     }
;   }
; }
	s_add_i32 s0, s2, s3
	s_add_i32 s0, s0, -4
	v_cmp_ge_i32_e32 vcc, s0, v130
	v_cmp_lt_i32_e64 s[0:1], s0, v131
	s_and_b64 s[80:81], vcc, s[0:1]
	s_and_saveexec_b64 s[0:1], s[80:81]
	ds_read_b32 v142, v139
	ds_read_b32 v143, v139 offset:4
	ds_read_b32 v110, v139 offset:8
	ds_read_b32 v111, v139 offset:12
	ds_read_b32 v107, v139 offset:32
	ds_read_b32 v108, v139 offset:36
	ds_read_b32 v105, v139 offset:40
	ds_read_b32 v106, v139 offset:44
	ds_read_b32 v102, v139 offset:64
	ds_read_b32 v103, v139 offset:68
	ds_read_b32 v100, v139 offset:72
	ds_read_b32 v101, v139 offset:76
	ds_read_b32 v98, v139 offset:96
	ds_read_b32 v99, v139 offset:100
	ds_read_b32 v96, v139 offset:104
	ds_read_b32 v97, v139 offset:108
	ds_read_b32 v158, v139 offset:128
	ds_read_b32 v109, v139 offset:132
	ds_read_b32 v144, v139 offset:136
	ds_read_b32 v145, v139 offset:140
	ds_read_b32 v146, v139 offset:160
	ds_read_b32 v147, v139 offset:164
	ds_read_b32 v148, v139 offset:168
	ds_read_b32 v149, v139 offset:172
	ds_read_b32 v150, v139 offset:192
	ds_read_b32 v151, v139 offset:196
	ds_read_b32 v152, v139 offset:200
	ds_read_b32 v153, v139 offset:204
	ds_read_b32 v154, v139 offset:224
	ds_read_b32 v155, v139 offset:228
	ds_read_b32 v156, v139 offset:232
	ds_read_b32 v157, v139 offset:236
	s_or_b64 exec, exec, s[0:1]
	s_waitcnt lgkmcnt(0)
	s_and_b64 vcc, s[70:71], s[80:81]
	v_fmamk_f32 v142, v142, 0x41000000, v48
	v_cndmask_b32_e32 v48, v248, v142, vcc
	s_and_b64 s[0:1], s[68:69], s[80:81]
	v_fmamk_f32 v143, v143, 0x41000000, v49
	v_cndmask_b32_e64 v49, v248, v143, s[0:1]
	s_and_b64 vcc, s[66:67], s[80:81]
	v_fmamk_f32 v110, v110, 0x41000000, v50
	v_cndmask_b32_e32 v50, v248, v110, vcc
	s_and_b64 s[0:1], s[64:65], s[80:81]
	v_fmamk_f32 v111, v111, 0x41000000, v51
	v_cndmask_b32_e64 v51, v248, v111, s[0:1]
	s_and_b64 vcc, s[62:63], s[80:81]
	v_fmamk_f32 v107, v107, 0x41000000, v52
	v_cndmask_b32_e32 v52, v248, v107, vcc
	s_and_b64 s[0:1], s[60:61], s[80:81]
	v_fmamk_f32 v108, v108, 0x41000000, v53
	v_cndmask_b32_e64 v53, v248, v108, s[0:1]
	s_and_b64 vcc, s[58:59], s[80:81]
	v_fmamk_f32 v105, v105, 0x41000000, v54
	v_cndmask_b32_e32 v54, v248, v105, vcc
	s_and_b64 s[0:1], s[56:57], s[80:81]
	v_fmamk_f32 v106, v106, 0x41000000, v55
	v_cndmask_b32_e64 v55, v248, v106, s[0:1]
	s_and_b64 vcc, s[54:55], s[80:81]
	v_fmamk_f32 v102, v102, 0x41000000, v56
	v_cndmask_b32_e32 v56, v248, v102, vcc
	s_and_b64 s[0:1], s[52:53], s[80:81]
	v_fmamk_f32 v103, v103, 0x41000000, v57
	v_cndmask_b32_e64 v57, v248, v103, s[0:1]
	s_and_b64 vcc, s[50:51], s[80:81]
	v_fmamk_f32 v100, v100, 0x41000000, v58
	v_cndmask_b32_e32 v58, v248, v100, vcc
	s_and_b64 s[0:1], s[48:49], s[80:81]
	v_fmamk_f32 v101, v101, 0x41000000, v59
	v_cndmask_b32_e64 v59, v248, v101, s[0:1]
	s_and_b64 vcc, s[46:47], s[80:81]
	v_fmamk_f32 v98, v98, 0x41000000, v60
	v_cndmask_b32_e32 v60, v248, v98, vcc
	s_and_b64 s[0:1], s[44:45], s[80:81]
	v_fmamk_f32 v99, v99, 0x41000000, v61
	v_cndmask_b32_e64 v61, v248, v99, s[0:1]
	s_and_b64 vcc, s[42:43], s[80:81]
	v_fmamk_f32 v96, v96, 0x41000000, v62
	v_cndmask_b32_e32 v62, v248, v96, vcc
	s_and_b64 s[0:1], s[40:41], s[80:81]
	v_fmamk_f32 v97, v97, 0x41000000, v63
	v_cndmask_b32_e64 v63, v248, v97, s[0:1]
	s_and_b64 vcc, s[6:7], s[80:81]
	v_fmamk_f32 v158, v158, 0x41000000, v32
	v_cndmask_b32_e32 v32, v248, v158, vcc
	s_and_b64 s[0:1], s[8:9], s[80:81]
	v_fmamk_f32 v109, v109, 0x41000000, v33
	v_cndmask_b32_e64 v33, v248, v109, s[0:1]
	s_and_b64 vcc, s[10:11], s[80:81]
	v_fmamk_f32 v144, v144, 0x41000000, v34
	v_cndmask_b32_e32 v34, v248, v144, vcc
	s_and_b64 s[0:1], s[12:13], s[80:81]
	v_fmamk_f32 v145, v145, 0x41000000, v35
	v_cndmask_b32_e64 v35, v248, v145, s[0:1]
	s_and_b64 vcc, s[14:15], s[80:81]
	v_fmamk_f32 v146, v146, 0x41000000, v36
	v_cndmask_b32_e32 v36, v248, v146, vcc
	s_and_b64 s[0:1], s[16:17], s[80:81]
	v_fmamk_f32 v147, v147, 0x41000000, v37
	v_cndmask_b32_e64 v37, v248, v147, s[0:1]
	s_and_b64 vcc, s[18:19], s[80:81]
	v_fmamk_f32 v148, v148, 0x41000000, v38
	v_cndmask_b32_e32 v38, v248, v148, vcc
	s_and_b64 s[0:1], s[20:21], s[80:81]
	v_fmamk_f32 v149, v149, 0x41000000, v39
	v_cndmask_b32_e64 v39, v248, v149, s[0:1]
	s_and_b64 vcc, s[22:23], s[80:81]
	v_fmamk_f32 v150, v150, 0x41000000, v40
	v_cndmask_b32_e32 v40, v248, v150, vcc
	s_and_b64 s[0:1], s[24:25], s[80:81]
	v_fmamk_f32 v151, v151, 0x41000000, v41
	v_cndmask_b32_e64 v41, v248, v151, s[0:1]
	s_and_b64 vcc, s[26:27], s[80:81]
	v_fmamk_f32 v152, v152, 0x41000000, v42
	v_cndmask_b32_e32 v42, v248, v152, vcc
	s_and_b64 s[0:1], s[28:29], s[80:81]
	v_fmamk_f32 v153, v153, 0x41000000, v43
	v_cndmask_b32_e64 v43, v248, v153, s[0:1]
	s_and_b64 vcc, s[30:31], s[80:81]
	v_fmamk_f32 v154, v154, 0x41000000, v44
	v_cndmask_b32_e32 v44, v248, v154, vcc
	s_and_b64 s[0:1], s[34:35], s[80:81]
	v_fmamk_f32 v155, v155, 0x41000000, v45
	v_cndmask_b32_e64 v45, v248, v155, s[0:1]
	s_and_b64 vcc, s[36:37], s[80:81]
	v_fmamk_f32 v156, v156, 0x41000000, v46
	v_cndmask_b32_e32 v46, v248, v156, vcc
	s_and_b64 s[0:1], s[38:39], s[80:81]
	v_fmamk_f32 v157, v157, 0x41000000, v47
	v_cndmask_b32_e64 v47, v248, v157, s[0:1]

; #define SBAR() __builtin_amdgcn_sched_barrier(0)
; template <int D0> __device__ __forceinline__ void pv_one(f32x16& od, int vb, bf16x8 pa0, bf16x8 pa1, bf16x8 pa2, bf16x8 pa3) {
;   const s16x4 l0 = tr_read<v_rd_off(D0, 0, 0)>(vb), h0 = tr_read<v_rd_off(D0, 0, 1)>(vb), l1 = tr_read<v_rd_off(D0, 1, 0)>(vb), h1 = tr_read<v_rd_off(D0, 1, 1)>(vb);
;   const s16x4 l2 = tr_read<v_rd_off(D0, 2, 0)>(vb), h2 = tr_read<v_rd_off(D0, 2, 1)>(vb), l3 = tr_read<v_rd_off(D0, 3, 0)>(vb), h3 = tr_read<v_rd_off(D0, 3, 1)>(vb);
;   asm volatile("s_waitcnt lgkmcnt(0)" ::: "memory"); SBAR();
;   od = __builtin_amdgcn_mfma_f32_32x32x16_bf16(pa0, PKLH(l0, h0), od, 0, 0, 0);
;   od = __builtin_amdgcn_mfma_f32_32x32x16_bf16(pa1, PKLH(l1, h1), od, 0, 0, 0);
;   od = __builtin_amdgcn_mfma_f32_32x32x16_bf16(pa2, PKLH(l2, h2), od, 0, 0, 0);
;   od = __builtin_amdgcn_mfma_f32_32x32x16_bf16(pa3, PKLH(l3, h3), od, 0, 0, 0);
; }
; __device__ __forceinline__ void pv_d0(f32x16* o, int vb, bf16x8 pa0, bf16x8 pa1, bf16x8 pa2, bf16x8 pa3) {
;   pv_one<0>(o[0], vb, pa0, pa1, pa2, pa3); pv_one<1>(o[1], vb, pa0, pa1, pa2, pa3);
; }
; __device__ __forceinline__ void na_bias(f32x16& p0, f32x16& p1, const NaInfo& na, int kr, int hi) {
;   const int rs = min(max(na.qr - 4, 0), 120);
;   if (kr < rs || kr >= rs + 8) {
; #pragma unroll
;     for (int r = 0; r < 16; ++r) { p0[r] = -1e30f; p1[r] = -1e30f; }
;   } else {
;     const float* b = na.brow + (kr - na.qr + 7) * 31 + (15 - na.qc) + 4 * hi;
;     const int ws = min(max(na.qc - 8, 0), 48) - 4 * hi;
; #pragma unroll
;     for (int r = 0; r < 16; ++r) {
;       const int kc0 = (r & 3) + 8 * (r >> 2);
;       const bool ok1 = (unsigned)(kc0 - ws) < 16u, ok2 = (unsigned)(kc0 + 32 - ws) < 16u;
;       const float b1 = b[kc0], b2 = b[kc0 + 32];
;       p0[r] = ok1 ? p0[r] + 8.0f * b1 : -1e30f;
;       p1[r] = ok2 ? p1[r] + 8.0f * b2 : -1e30f;
;       if ((r & 3) == 3) SBAR();
;     }
;   }
; }
.LBB0_823:
	ds_read_b64_tr_b16 v[146:147], v123 offset:0
	ds_read_b64_tr_b16 v[148:149], v123 offset:0x800
	ds_read_b64_tr_b16 v[150:151], v123 offset:0x1000
	ds_read_b64_tr_b16 v[152:153], v123 offset:0x1800
	ds_read_b64_tr_b16 v[154:155], v123 offset:0x2000
	ds_read_b64_tr_b16 v[156:157], v123 offset:0x2800
	ds_read_b64_tr_b16 v[158:159], v123 offset:0x3000
	ds_read_b64_tr_b16 v[160:161], v123 offset:0x3800
	s_waitcnt lgkmcnt(0)
	s_nop 0
	v_mfma_f32_32x32x16_bf16 v[0:15], v[96:99], v[146:149], v[0:15]
	ds_read_b64_tr_b16 v[146:147], v123 offset:0x200
	ds_read_b64_tr_b16 v[148:149], v123 offset:0xa00
	v_mfma_f32_32x32x16_bf16 v[0:15], v[100:103], v[150:153], v[0:15]
	ds_read_b64_tr_b16 v[150:151], v123 offset:0x1200
	ds_read_b64_tr_b16 v[152:153], v123 offset:0x1a00
	v_mfma_f32_32x32x16_bf16 v[0:15], v[104:107], v[154:157], v[0:15]
	ds_read_b64_tr_b16 v[154:155], v123 offset:0x2200
	ds_read_b64_tr_b16 v[156:157], v123 offset:0x2a00
	v_mfma_f32_32x32x16_bf16 v[0:15], v[108:111], v[158:161], v[0:15]
	ds_read_b64_tr_b16 v[158:159], v123 offset:0x3200
	ds_read_b64_tr_b16 v[160:161], v123 offset:0x3a00
	s_waitcnt lgkmcnt(0)
	v_mfma_f32_32x32x16_bf16 v[16:31], v[96:99], v[146:149], v[16:31]
	v_mfma_f32_32x32x16_bf16 v[16:31], v[100:103], v[150:153], v[16:31]
	v_mfma_f32_32x32x16_bf16 v[16:31], v[104:107], v[154:157], v[16:31]
	v_mfma_f32_32x32x16_bf16 v[16:31], v[108:111], v[158:161], v[16:31]
	s_cmp_lt_u32 s3, 3
	s_cbranch_scc1 .LBB0_859
	s_add_i32 s0, s2, s3
	s_add_i32 s0, s0, -3
	v_cmp_ge_i32_e32 vcc, s0, v130
	v_cmp_lt_i32_e64 s[0:1], s0, v131
	s_and_b64 s[82:83], vcc, s[0:1]
	s_and_saveexec_b64 s[0:1], s[82:83]
	ds_read_b32 v105, v139 offset:124
	ds_read_b32 v147, v139 offset:128
	ds_read_b32 v148, v139 offset:132
	ds_read_b32 v149, v139 offset:136
	ds_read_b32 v150, v139 offset:156
	ds_read_b32 v151, v139 offset:160
	ds_read_b32 v152, v139 offset:164
	ds_read_b32 v153, v139 offset:168
	ds_read_b32 v154, v139 offset:188
	ds_read_b32 v155, v139 offset:192
	ds_read_b32 v156, v139 offset:196
	ds_read_b32 v157, v139 offset:200
	ds_read_b32 v158, v139 offset:220
	ds_read_b32 v159, v139 offset:224
	ds_read_b32 v160, v139 offset:228
	ds_read_b32 v161, v139 offset:232
	ds_read_b32 v111, v139 offset:252
	ds_read_b32 v146, v139 offset:256
	ds_read_b32 v109, v139 offset:260
	ds_read_b32 v110, v139 offset:264
	ds_read_b32 v107, v139 offset:284
	ds_read_b32 v108, v139 offset:288
	ds_read_b32 v104, v139 offset:292
	ds_read_b32 v106, v139 offset:296
	ds_read_b32 v102, v139 offset:316
	ds_read_b32 v103, v139 offset:320
	ds_read_b32 v100, v139 offset:324
	ds_read_b32 v101, v139 offset:328
	ds_read_b32 v98, v139 offset:348
	ds_read_b32 v99, v139 offset:352
	ds_read_b32 v96, v139 offset:356
	ds_read_b32 v97, v139 offset:360
	s_or_b64 exec, exec, s[0:1]
	s_waitcnt lgkmcnt(0)
	s_and_b64 vcc, s[70:71], s[82:83]
	v_fmamk_f32 v105, v105, 0x41000000, v48
	v_cndmask_b32_e32 v48, v248, v105, vcc
	s_and_b64 s[0:1], s[68:69], s[82:83]
	v_fmamk_f32 v147, v147, 0x41000000, v49
	v_cndmask_b32_e64 v49, v248, v147, s[0:1]
	s_and_b64 vcc, s[66:67], s[82:83]
	v_fmamk_f32 v148, v148, 0x41000000, v50
	v_cndmask_b32_e32 v50, v248, v148, vcc
	s_and_b64 s[0:1], s[64:65], s[82:83]
	v_fmamk_f32 v149, v149, 0x41000000, v51
	v_cndmask_b32_e64 v51, v248, v149, s[0:1]
	s_and_b64 vcc, s[62:63], s[82:83]
	v_fmamk_f32 v150, v150, 0x41000000, v52
	v_cndmask_b32_e32 v52, v248, v150, vcc
	s_and_b64 s[0:1], s[60:61], s[82:83]
	v_fmamk_f32 v151, v151, 0x41000000, v53
	v_cndmask_b32_e64 v53, v248, v151, s[0:1]
	s_and_b64 vcc, s[58:59], s[82:83]
	v_fmamk_f32 v152, v152, 0x41000000, v54
	v_cndmask_b32_e32 v54, v248, v152, vcc
	s_and_b64 s[0:1], s[56:57], s[82:83]
	v_fmamk_f32 v153, v153, 0x41000000, v55
	v_cndmask_b32_e64 v55, v248, v153, s[0:1]
	s_and_b64 vcc, s[54:55], s[82:83]
	v_fmamk_f32 v154, v154, 0x41000000, v56
	v_cndmask_b32_e32 v56, v248, v154, vcc
	s_and_b64 s[0:1], s[52:53], s[82:83]
	v_fmamk_f32 v155, v155, 0x41000000, v57
	v_cndmask_b32_e64 v57, v248, v155, s[0:1]
	s_and_b64 vcc, s[50:51], s[82:83]
	v_fmamk_f32 v156, v156, 0x41000000, v58
	v_cndmask_b32_e32 v58, v248, v156, vcc
	s_and_b64 s[0:1], s[48:49], s[82:83]
	v_fmamk_f32 v157, v157, 0x41000000, v59
	v_cndmask_b32_e64 v59, v248, v157, s[0:1]
	s_and_b64 vcc, s[46:47], s[82:83]
	v_fmamk_f32 v158, v158, 0x41000000, v60
	v_cndmask_b32_e32 v60, v248, v158, vcc
	s_and_b64 s[0:1], s[44:45], s[82:83]
	v_fmamk_f32 v159, v159, 0x41000000, v61
	v_cndmask_b32_e64 v61, v248, v159, s[0:1]
	s_and_b64 vcc, s[42:43], s[82:83]
	v_fmamk_f32 v160, v160, 0x41000000, v62
	v_cndmask_b32_e32 v62, v248, v160, vcc
	s_and_b64 s[0:1], s[40:41], s[82:83]
	v_fmamk_f32 v161, v161, 0x41000000, v63
	v_cndmask_b32_e64 v63, v248, v161, s[0:1]
	s_and_b64 vcc, s[6:7], s[82:83]
	v_fmamk_f32 v111, v111, 0x41000000, v32
	v_cndmask_b32_e32 v32, v248, v111, vcc
	s_and_b64 s[0:1], s[8:9], s[82:83]
	v_fmamk_f32 v146, v146, 0x41000000, v33
	v_cndmask_b32_e64 v33, v248, v146, s[0:1]
	s_and_b64 vcc, s[10:11], s[82:83]
	v_fmamk_f32 v109, v109, 0x41000000, v34
	v_cndmask_b32_e32 v34, v248, v109, vcc
	s_and_b64 s[0:1], s[12:13], s[82:83]
	v_fmamk_f32 v110, v110, 0x41000000, v35
	v_cndmask_b32_e64 v35, v248, v110, s[0:1]
	s_and_b64 vcc, s[14:15], s[82:83]
	v_fmamk_f32 v107, v107, 0x41000000, v36
	v_cndmask_b32_e32 v36, v248, v107, vcc
	s_and_b64 s[0:1], s[16:17], s[82:83]
	v_fmamk_f32 v108, v108, 0x41000000, v37
	v_cndmask_b32_e64 v37, v248, v108, s[0:1]
	s_and_b64 vcc, s[18:19], s[82:83]
	v_fmamk_f32 v104, v104, 0x41000000, v38
	v_cndmask_b32_e32 v38, v248, v104, vcc
	s_and_b64 s[0:1], s[20:21], s[82:83]
	v_fmamk_f32 v106, v106, 0x41000000, v39
	v_cndmask_b32_e64 v39, v248, v106, s[0:1]
	s_and_b64 vcc, s[22:23], s[82:83]
	v_fmamk_f32 v102, v102, 0x41000000, v40
	v_cndmask_b32_e32 v40, v248, v102, vcc
	s_and_b64 s[0:1], s[24:25], s[82:83]
	v_fmamk_f32 v103, v103, 0x41000000, v41
	v_cndmask_b32_e64 v41, v248, v103, s[0:1]
	s_and_b64 vcc, s[26:27], s[82:83]
	v_fmamk_f32 v100, v100, 0x41000000, v42
	v_cndmask_b32_e32 v42, v248, v100, vcc
	s_and_b64 s[0:1], s[28:29], s[82:83]
	v_fmamk_f32 v101, v101, 0x41000000, v43
	v_cndmask_b32_e64 v43, v248, v101, s[0:1]
	s_and_b64 vcc, s[30:31], s[82:83]
	v_fmamk_f32 v98, v98, 0x41000000, v44
	v_cndmask_b32_e32 v44, v248, v98, vcc
	s_and_b64 s[0:1], s[34:35], s[82:83]
	v_fmamk_f32 v99, v99, 0x41000000, v45
	v_cndmask_b32_e64 v45, v248, v99, s[0:1]
	s_and_b64 vcc, s[36:37], s[82:83]
	v_fmamk_f32 v96, v96, 0x41000000, v46
	v_cndmask_b32_e32 v46, v248, v96, vcc
	s_and_b64 s[0:1], s[38:39], s[82:83]
	v_fmamk_f32 v97, v97, 0x41000000, v47
	v_cndmask_b32_e64 v47, v248, v97, s[0:1]
